# dependency relaxation: grid barrier 1 replaced by a GEMV-completion counter wait (phase 1 only needs mod)
# baseline (speedup 1.0000x reference)
.LBB0_109:
	s_or_b64 exec, exec, s[20:21]
	s_waitcnt vmcnt(0)
	s_barrier
	v_cmp_eq_u32_e32 vcc, 0, v0
	s_and_saveexec_b64 s[20:21], vcc
	v_mov_b32_e32 v230, 0x3f20
	v_mov_b32_e32 v231, 1
	global_atomic_add v230, v231, s[88:89]
	s_or_b64 exec, exec, s[20:21]
	s_mov_b64 s[22:23], -1

.LBB0_113:
	s_waitcnt vmcnt(0)
	s_barrier
	s_and_saveexec_b64 s[0:1], s[24:25]
	s_cbranch_execz .LBB0_165
	v_mov_b32_e32 v230, 0x3f20
	s_mov_b32 s4, 0
.Lb1_poll:
	global_load_dword v231, v230, s[88:89] sc1
	s_waitcnt vmcnt(0)
	v_readfirstlane_b32 s3, v231
	s_cmpk_gt_u32 s3, 0x17f
	s_cbranch_scc1 .Lb1_done
	s_add_u32 s4, s4, 1
	s_cmp_gt_u32 s4, 0x40000
	s_cbranch_scc1 .Lb1_done
	s_sleep 1
	s_branch .Lb1_poll
.Lb1_done:
	buffer_inv sc1
	s_waitcnt vmcnt(0)
.LBB0_165:
	s_or_b64 exec, exec, s[0:1]
	v_mov_b32_e32 v3, v0
	s_waitcnt lgkmcnt(0)
	s_barrier
	s_lshl_b32 s26, s2, 2
	v_ashrrev_i32_e32 v2, 6, v3
	v_add_u32_e32 v35, s26, v2
	s_movk_i32 s0, 0x3000
	s_lshl_b32 s28, s99, 2
	v_cmp_gt_i32_e32 vcc, s0, v35
	v_mbcnt_lo_u32_b32 v1, -1, 0
	s_and_saveexec_b64 s[0:1], vcc
	s_cbranch_execz .LBB0_174
	v_and_b32_e32 v4, 63, v3
	v_mbcnt_hi_u32_b32 v3, -1, v1
	v_and_b32_e32 v5, 64, v3
	v_add_u32_e32 v5, 64, v5
	v_xor_b32_e32 v6, 32, v3
	v_cmp_lt_i32_e32 vcc, v6, v5
	s_ashr_i32 s27, s26, 31
	v_lshlrev_b32_e32 v18, 3, v4
	v_cndmask_b32_e32 v6, v3, v6, vcc
	v_lshlrev_b32_e32 v42, 2, v6
	v_xor_b32_e32 v6, 16, v3
	v_cmp_lt_i32_e32 vcc, v6, v5
	v_mov_b32_e32 v19, 0
	s_ashr_i32 s29, s28, 31
	v_cndmask_b32_e32 v6, v3, v6, vcc
	v_lshlrev_b32_e32 v43, 2, v6
	v_xor_b32_e32 v6, 8, v3
	v_cmp_lt_i32_e32 vcc, v6, v5
	v_lshl_add_u64 v[20:21], s[48:49], 0, v[18:19]
	s_lshl_b64 s[4:5], s[28:29], 12
	v_cndmask_b32_e32 v6, v3, v6, vcc
	v_lshlrev_b32_e32 v44, 2, v6
	v_xor_b32_e32 v6, 4, v3
	v_cmp_lt_i32_e32 vcc, v6, v5
	s_lshl_b64 s[6:7], s[28:29], 11
	s_mov_b64 s[8:9], 0
	v_cndmask_b32_e32 v6, v3, v6, vcc
	v_lshlrev_b32_e32 v45, 2, v6
	v_xor_b32_e32 v6, 2, v3
	v_cmp_lt_i32_e32 vcc, v6, v5
	s_movk_i32 s3, 0x1fff
	s_movk_i32 s13, 0xc00
	v_cndmask_b32_e32 v6, v3, v6, vcc
	v_lshlrev_b32_e32 v46, 2, v6
	v_xor_b32_e32 v6, 1, v3
	v_cmp_lt_i32_e32 vcc, v6, v5
	s_movk_i32 s16, 0xefff
	s_mov_b64 s[10:11], 0x1000
	v_cndmask_b32_e32 v3, v3, v6, vcc
	v_lshlrev_b32_e32 v47, 2, v3
	v_ashrrev_i32_e32 v3, 31, v2
	v_lshl_add_u64 v[2:3], v[2:3], 0, s[26:27]
	v_lshlrev_b32_e32 v6, 2, v4
	v_lshlrev_b64 v[14:15], 12, v[2:3]
	v_lshlrev_b64 v[2:3], 11, v[2:3]
	v_or_b32_e32 v8, 0x100, v6
	v_or_b32_e32 v10, 0x200, v6
	v_or_b32_e32 v12, 0x300, v6
	v_or_b32_e32 v2, v2, v18
	v_lshl_add_u64 v[22:23], s[56:57], 0, v[14:15]
	v_lshl_add_u64 v[24:25], s[48:49], 0, v[2:3]
	v_lshlrev_b32_e32 v18, 4, v4
	v_lshlrev_b32_e32 v26, 2, v6
	v_lshlrev_b32_e32 v28, 2, v8
	v_lshlrev_b32_e32 v30, 2, v10
	v_lshlrev_b32_e32 v32, 2, v12
	s_mov_b32 s12, 0x3a800000
	s_mov_b32 s17, 0x800000
	s_movk_i32 s18, 0x2fff
	v_mov_b32_e32 v34, 0x358637bd
	s_branch .LBB0_168
